# P2 tail: waves 4-7 run one statically assigned sample S5 item before their pass-2 chunk and waves 0-3 after it (the two waves of a SIMD overlap latency-bound and VALU-bound work); dynamic pool = the o
# speedup vs baseline: 1.0405x; 1.0027x over previous
.LBB0_1043:
	s_mov_b32 s100, 0
	v_readlane_b32 s0, v252, 4
	v_readlane_b32 s2, v252, 6
	v_readlane_b32 s3, v252, 7
	v_readlane_b32 s93, v252, 59
	s_mov_b64 s[72:73], s[2:3]
	s_cmp_lt_u32 s93, 64
	v_readlane_b32 s1, v252, 5
	s_cbranch_scc0 .LBB0_1055
	s_memrealtime s[0:1]
	s_add_u32 s4, s72, 0x8000
	s_addc_u32 s5, s73, 0
	v_mov_b32_e32 v4, 0
	s_waitcnt lgkmcnt(0)
	v_mov_b64_e32 v[2:3], 0x1e8481
	s_branch .LBB0_1047

.LBB0_1055:
	s_waitcnt vmcnt(0)
	v_cmp_ne_u32_e32 vcc, 1, v1
	s_waitcnt lgkmcnt(0)
	s_barrier
	s_cbranch_vccnz .LBB0_1065
	v_readlane_b32 s0, v252, 47
	s_bitcmp1_b32 s100, 0
	s_cbranch_scc1 .Lp2_setup_go
	s_cmp_lt_u32 s0, 4
	s_cbranch_scc1 .Lp2_setup_go
	s_or_b32 s100, s100, 4
	s_branch .Lsmp_static
.Lp2_setup_go:
	v_readlane_b32 s0, v252, 47
	s_mulk_i32 s0, 0x3000
	s_add_i32 s3, s0, 0
	s_add_u32 s39, s72, 0xb300000
	s_addc_u32 s63, s73, 0
	s_add_u32 s74, s72, 0xd500000
	s_addc_u32 s75, s73, 0
	s_add_u32 s0, s72, 0xc00000
	s_addc_u32 s1, s73, 0
	s_add_u32 s46, s72, 0xb55000
	s_addc_u32 s47, s73, 0
	s_add_u32 s52, s72, 0xb01000
	v_writelane_b32 v251, s0, 2
	s_addc_u32 s53, s73, 0
	s_mov_b32 s31, 0
	v_writelane_b32 v251, s1, 3
	s_add_u32 s0, s72, 0xb11000
	s_addc_u32 s1, s73, 0
	v_writelane_b32 v251, s0, 4
	s_add_u32 s58, s72, 0xb75000
	s_addc_u32 s59, s73, 0
	v_writelane_b32 v251, s1, 5
	v_readlane_b32 s0, v252, 56
	s_bitcmp1_b32 s0, 1
	s_cselect_b64 s[0:1], -1, 0
	v_writelane_b32 v252, s0, 61
	v_mov_b32_e32 v147, 0
	s_nop 0
	v_writelane_b32 v252, s1, 62
	s_branch .LBB0_1058

.LBB0_1065:
	s_bitcmp1_b32 s100, 0
	s_cbranch_scc1 .Lsmp_dyn
	s_branch .Lsmp_static

.LBB0_1069:
	s_or_b64 exec, exec, s[0:1]
	s_add_i32 s0, 0, 0x20170
	v_mov_b32_e32 v1, s0
	s_waitcnt lgkmcnt(0)
	s_barrier
	ds_read_b32 v1, v1
	s_movk_i32 s0, 0xff
	s_mov_b32 s53, 0
	s_waitcnt lgkmcnt(0)
	v_cmp_lt_u32_e32 vcc, s0, v1
	v_readfirstlane_b32 s52, v1
	s_cbranch_vccnz .LBB0_1084
	s_add_u32 s54, s72, 0xb01000
	s_addc_u32 s55, s73, 0
	s_add_u32 s56, s72, 0xb15000
	s_addc_u32 s57, s73, 0
	v_readlane_b32 s3, v252, 56
	v_ashrrev_i32_e32 v19, 31, v18
	s_bitcmp1_b32 s3, 2
	s_cselect_b64 s[58:59], -1, 0
	s_add_u32 s3, s72, 0xc300010
	v_lshl_add_u64 v[2:3], v[18:19], 1, s[72:73]
	s_mov_b64 s[4:5], 0xe500000
	v_and_b32_e32 v1, 15, v18
	v_cmp_gt_i32_e64 s[0:1], 16, v18
	v_cmp_eq_u32_e64 s[38:39], 15, v18
	v_and_b32_e32 v49, 8, v18
	v_cmp_ne_u32_e64 s[6:7], 0, v49
	v_and_b32_e32 v49, 4, v18
	v_cmp_ne_u32_e64 s[8:9], 0, v49
	v_and_b32_e32 v49, 2, v18
	v_cmp_ne_u32_e64 s[10:11], 0, v49
	v_and_b32_e32 v49, 1, v18
	v_cmp_ne_u32_e64 s[12:13], 0, v49
	v_and_b32_e32 v106, 15, v18
	v_lshlrev_b32_e32 v106, 1, v106
	v_cmp_eq_u32_e64 s[14:15], 10, v18
	v_cmp_eq_u32_e64 s[16:17], 9, v18
	v_cmp_eq_u32_e64 s[18:19], 8, v18
	v_cmp_eq_u32_e64 s[20:21], 7, v18
	v_cmp_eq_u32_e64 s[22:23], 6, v18
	v_cmp_eq_u32_e64 s[24:25], 5, v18
	v_cmp_eq_u32_e64 s[26:27], 4, v18
	v_cmp_eq_u32_e64 s[28:29], 3, v18
	v_cmp_eq_u32_e64 s[30:31], 2, v18
	s_mov_b32 s2, 1
	v_cmp_eq_u32_e64 s[34:35], 1, v18
	v_cmp_eq_u32_e64 s[36:37], 0, v18
	s_addc_u32 s33, s73, 0
	v_lshl_add_u64 v[20:21], v[2:3], 0, s[4:5]
	v_mov_b32_e32 v47, 0
	s_movk_i32 s62, 0x100
	s_branch .LBB0_1072

.Lsmp_item:
	s_lshl_b32 s4, s52, 3
	s_add_i32 s4, s4, s67
	s_addk_i32 s4, 0x800
	s_and_b32 s5, s4, 31
	s_lshl_b32 s44, s5, 6
	v_add_u32_e32 v22, s44, v18
	s_lshr_b32 s52, s4, 5
	v_ashrrev_i32_e32 v23, 31, v22
	s_mul_i32 s4, s5, 0x3c0
	v_lshlrev_b64 v[2:3], 5, v[22:23]
	v_lshlrev_b64 v[4:5], 7, v[22:23]
	v_add_u32_e32 v22, s4, v22
	v_readlane_b32 s68, v252, 24
	v_ashrrev_i32_e32 v23, 31, v22
	v_readlane_b32 s69, v252, 25
	v_readlane_b32 s70, v252, 26
	v_readlane_b32 s71, v252, 27
	v_readlane_b32 s80, v252, 36
	v_readlane_b32 s81, v252, 37
	v_lshlrev_b64 v[22:23], 2, v[22:23]
	v_readlane_b32 s82, v252, 38
	v_readlane_b32 s83, v252, 39
	s_mov_b64 s[68:69], s[80:81]
	v_lshl_add_u64 v[2:3], s[54:55], 0, v[2:3]
	v_lshl_add_u64 v[14:15], s[56:57], 0, v[4:5]
	s_mov_b64 s[70:71], s[82:83]
	v_lshl_add_u64 v[24:25], s[68:69], 0, v[22:23]
	global_load_dwordx2 v[44:45], v[2:3], off
	global_load_dwordx4 v[98:101], v[14:15], off
	global_load_dwordx4 v[40:43], v[14:15], off offset:16
	global_load_dwordx4 v[36:39], v[14:15], off offset:32
	global_load_dwordx4 v[32:35], v[14:15], off offset:48
	s_nop 0
	global_load_dwordx4 v[2:5], v[14:15], off offset:64
	global_load_dwordx4 v[6:9], v[14:15], off offset:80
	global_load_dwordx4 v[10:13], v[14:15], off offset:96
	s_nop 0
	global_load_dwordx4 v[14:17], v[14:15], off offset:112
	v_lshl_add_u64 v[22:23], s[70:71], 0, v[22:23]
	global_load_dword v51, v[24:25], off
	global_load_dword v53, v[24:25], off offset:256
	global_load_dword v55, v[24:25], off offset:512
	global_load_dword v57, v[24:25], off offset:768
	global_load_dword v59, v[24:25], off offset:1024
	global_load_dword v61, v[24:25], off offset:1280
	global_load_dword v63, v[24:25], off offset:1536
	global_load_dword v65, v[24:25], off offset:1792
	global_load_dword v67, v[22:23], off
	global_load_dword v69, v[22:23], off offset:256
	global_load_dword v71, v[22:23], off offset:512
	global_load_dword v73, v[22:23], off offset:768
	global_load_dword v75, v[22:23], off offset:1024
	global_load_dword v77, v[22:23], off offset:1280
	global_load_dword v78, v[22:23], off offset:1536
	global_load_dword v79, v[22:23], off offset:1792
	global_load_dword v80, v[24:25], off offset:2048
	global_load_dword v81, v[24:25], off offset:2304
	global_load_dword v82, v[24:25], off offset:2560
	global_load_dword v83, v[24:25], off offset:2816
	global_load_dword v84, v[24:25], off offset:3072
	global_load_dword v85, v[24:25], off offset:3328
	global_load_dword v86, v[24:25], off offset:3584
	global_load_dword v87, v[24:25], off offset:3840
	global_load_dword v88, v[22:23], off offset:2048
	global_load_dword v89, v[22:23], off offset:2304
	global_load_dword v90, v[22:23], off offset:2560
	global_load_dword v91, v[22:23], off offset:2816
	global_load_dword v92, v[22:23], off offset:3072
	global_load_dword v93, v[22:23], off offset:3328
	global_load_dword v94, v[22:23], off offset:3584
	global_load_dword v95, v[22:23], off offset:3840
	s_lshl_b32 s4, s52, 11
	s_or_b32 s4, s44, s4
	v_add_u32_e32 v22, s4, v18
	v_ashrrev_i32_e32 v23, 31, v22
	v_readlane_b32 s76, v252, 32
	v_readlane_b32 s77, v252, 33
	v_readlane_b32 s78, v252, 34
	v_readlane_b32 s79, v252, 35
	v_lshlrev_b64 v[24:25], 2, v[22:23]
	v_lshl_add_u64 v[22:23], s[48:49], 0, v[24:25]
	v_readlane_b32 s76, v252, 48
	global_load_dword v23, v[22:23], off
	v_lshl_or_b32 v22, v1, 2, s44
	v_readlane_b32 s77, v252, 49
	v_lshl_add_u64 v[24:25], s[50:51], 0, v[24:25]
	s_nop 3
	global_load_dword v96, v22, s[76:77]
	s_nop 0
	global_load_dword v22, v[24:25], off
	s_lshl_b64 s[44:45], s[52:53], 12
	s_lshl_b32 s5, s5, 5
	s_or_b32 s44, s44, s5
	s_add_u32 s5, s3, s44
	s_addc_u32 s52, s33, s45
	s_mov_b32 s60, s5
	s_mov_b32 s61, s52
	global_load_dwordx4 v[162:165], v47, s[60:61] offset:-16
	global_load_dwordx4 v[166:169], v47, s[60:61] offset:0
	global_load_ushort v170, v106, s[60:61] offset:-16
	global_load_dwordx4 v[130:133], v47, s[60:61] offset:1008
	global_load_dwordx4 v[134:137], v47, s[60:61] offset:1024
	global_load_ushort v171, v106, s[60:61] offset:1008
	global_load_dwordx4 v[138:141], v47, s[60:61] offset:2032
	global_load_dwordx4 v[142:145], v47, s[60:61] offset:2048
	global_load_ushort v172, v106, s[60:61] offset:2032
	global_load_dwordx4 v[150:153], v47, s[60:61] offset:3056
	global_load_dwordx4 v[154:157], v47, s[60:61] offset:3072
	global_load_ushort v173, v106, s[60:61] offset:3056
	v_readlane_b32 s72, v252, 28
	v_readlane_b32 s73, v252, 29
	v_readlane_b32 s74, v252, 30
	v_readlane_b32 s75, v252, 31
	v_readlane_b32 s78, v252, 50
	v_readlane_b32 s79, v252, 51
	v_readlane_b32 s80, v252, 52
	v_readlane_b32 s81, v252, 53
	v_readlane_b32 s82, v252, 54
	v_readlane_b32 s83, v252, 55
	s_waitcnt vmcnt(55)
	v_pk_add_f32 v[26:27], v[44:45], 0 neg_lo:[1,1] neg_hi:[1,1]
	v_mov_b32_e32 v24, v44
	v_mov_b32_e32 v25, v44
	v_mov_b32_e32 v26, v45
	s_waitcnt vmcnt(51)
	v_mov_b32_e32 v29, v35
	v_mov_b32_e32 v31, v33
	v_mov_b32_e32 v33, v39
	v_mov_b32_e32 v35, v37
	s_waitcnt vmcnt(47)
	v_mov_b32_e32 v28, v17
	v_mov_b32_e32 v17, v34
	v_mov_b32_e32 v30, v15
	v_mov_b32_e32 v15, v32
	v_mov_b32_e32 v32, v13
	v_mov_b32_e32 v13, v38
	v_mov_b32_e32 v34, v11
	v_mov_b32_e32 v11, v36
	v_mov_b32_e32 v36, v9
	v_mov_b32_e32 v37, v43
	v_mov_b32_e32 v9, v42
	v_mov_b32_e32 v38, v7
	v_mov_b32_e32 v39, v41
	v_mov_b32_e32 v7, v40
	v_mov_b32_e32 v40, v5
	v_mov_b32_e32 v41, v101
	v_mov_b32_e32 v5, v100
	v_mov_b32_e32 v42, v3
	v_mov_b32_e32 v43, v99
	v_mov_b32_e32 v3, v98
	v_lshl_add_u64 v[44:45], v[20:21], 0, s[44:45]
	s_mov_b64 s[44:45], 0
	s_waitcnt vmcnt(0)
	v_lshlrev_b32_e32 v46, 16, v162
	v_and_b32_e32 v48, 0xffff0000, v162
	v_lshlrev_b32_e32 v50, 16, v163
	v_and_b32_e32 v52, 0xffff0000, v163
	v_pk_fma_f32 v[98:99], v[2:3], v[46:47], 0 op_sel_hi:[1,0,0]
	v_lshlrev_b32_e32 v54, 16, v164
	v_pk_fma_f32 v[98:99], v[42:43], v[48:49], v[98:99] op_sel_hi:[1,0,1]
	v_and_b32_e32 v56, 0xffff0000, v164
	v_pk_fma_f32 v[98:99], v[4:5], v[50:51], v[98:99] op_sel_hi:[1,0,1]
	v_lshlrev_b32_e32 v58, 16, v165
	v_pk_fma_f32 v[98:99], v[40:41], v[52:53], v[98:99] op_sel_hi:[1,0,1]
	v_and_b32_e32 v60, 0xffff0000, v165
	v_pk_fma_f32 v[98:99], v[6:7], v[54:55], v[98:99] op_sel_hi:[1,0,1]
	v_lshlrev_b32_e32 v62, 16, v166
	v_pk_fma_f32 v[98:99], v[38:39], v[56:57], v[98:99] op_sel_hi:[1,0,1]
	v_and_b32_e32 v64, 0xffff0000, v166
	v_pk_fma_f32 v[98:99], v[8:9], v[58:59], v[98:99] op_sel_hi:[1,0,1]
	v_lshlrev_b32_e32 v66, 16, v167
	v_pk_fma_f32 v[98:99], v[36:37], v[60:61], v[98:99] op_sel_hi:[1,0,1]
	v_and_b32_e32 v68, 0xffff0000, v167
	v_pk_fma_f32 v[98:99], v[10:11], v[62:63], v[98:99] op_sel_hi:[1,0,1]
	v_lshlrev_b32_e32 v70, 16, v168
	v_pk_fma_f32 v[98:99], v[34:35], v[64:65], v[98:99] op_sel_hi:[1,0,1]
	v_and_b32_e32 v72, 0xffff0000, v168
	v_pk_fma_f32 v[98:99], v[12:13], v[66:67], v[98:99] op_sel_hi:[1,0,1]
	v_lshlrev_b32_e32 v74, 16, v169
	v_pk_fma_f32 v[98:99], v[32:33], v[68:69], v[98:99] op_sel_hi:[1,0,1]
	v_and_b32_e32 v76, 0xffff0000, v169
	v_pk_fma_f32 v[98:99], v[14:15], v[70:71], v[98:99] op_sel_hi:[1,0,1]
	s_nop 0
	v_pk_fma_f32 v[98:99], v[30:31], v[72:73], v[98:99] op_sel_hi:[1,0,1]
	s_nop 0
	v_pk_fma_f32 v[98:99], v[16:17], v[74:75], v[98:99] op_sel_hi:[1,0,1]
	s_nop 0
	v_pk_fma_f32 v[98:99], v[28:29], v[76:77], v[98:99] op_sel_hi:[1,0,1]
	s_nop 0
	v_pk_fma_f32 v[98:99], v[26:27], v[22:23], v[98:99] op_sel:[0,1,0] op_sel_hi:[1,0,1]
	s_nop 0
	v_pk_fma_f32 v[22:23], v[24:25], v[22:23], v[98:99]
	s_nop 0
	v_mul_f32_e32 v97, v67, v22
	v_mul_f32_e32 v98, v69, v22
	v_mul_f32_e32 v99, v71, v22
	v_mul_f32_e32 v100, v73, v22
	v_mul_f32_e32 v101, v75, v22
	v_mul_f32_e32 v102, v77, v22
	v_mul_f32_e32 v109, v78, v22
	v_mul_f32_e32 v111, v79, v22
	v_mul_f32_e32 v113, v88, v22
	v_mul_f32_e32 v115, v89, v22
	v_mul_f32_e32 v117, v90, v22
	v_mul_f32_e32 v119, v91, v22
	v_mul_f32_e32 v121, v92, v22
	v_mul_f32_e32 v123, v93, v22
	v_mul_f32_e32 v125, v94, v22
	v_mul_f32_e32 v127, v95, v22
	v_fma_f32 v97, v51, v23, -v97
	v_fma_f32 v98, v53, v23, -v98
	v_fma_f32 v99, v55, v23, -v99
	v_fma_f32 v100, v57, v23, -v100
	v_fma_f32 v101, v59, v23, -v101
	v_fma_f32 v102, v61, v23, -v102
	v_fma_f32 v109, v63, v23, -v109
	v_fma_f32 v111, v65, v23, -v111
	v_fma_f32 v113, v80, v23, -v113
	v_fma_f32 v115, v81, v23, -v115
	v_fma_f32 v117, v82, v23, -v117
	v_fma_f32 v119, v83, v23, -v119
	v_fma_f32 v121, v84, v23, -v121
	v_fma_f32 v123, v85, v23, -v123
	v_fma_f32 v125, v86, v23, -v125
	v_fma_f32 v127, v87, v23, -v127
	v_add_f32_dpp v97, v97, v97 row_ror:8 row_mask:0xf bank_mask:0xf bound_ctrl:1
	v_add_f32_dpp v98, v98, v98 row_ror:8 row_mask:0xf bank_mask:0xf bound_ctrl:1
	v_add_f32_dpp v99, v99, v99 row_ror:8 row_mask:0xf bank_mask:0xf bound_ctrl:1
	v_add_f32_dpp v100, v100, v100 row_ror:8 row_mask:0xf bank_mask:0xf bound_ctrl:1
	v_add_f32_dpp v101, v101, v101 row_ror:8 row_mask:0xf bank_mask:0xf bound_ctrl:1
	v_add_f32_dpp v102, v102, v102 row_ror:8 row_mask:0xf bank_mask:0xf bound_ctrl:1
	v_add_f32_dpp v109, v109, v109 row_ror:8 row_mask:0xf bank_mask:0xf bound_ctrl:1
	v_add_f32_dpp v111, v111, v111 row_ror:8 row_mask:0xf bank_mask:0xf bound_ctrl:1
	v_add_f32_dpp v113, v113, v113 row_ror:8 row_mask:0xf bank_mask:0xf bound_ctrl:1
	v_add_f32_dpp v115, v115, v115 row_ror:8 row_mask:0xf bank_mask:0xf bound_ctrl:1
	v_add_f32_dpp v117, v117, v117 row_ror:8 row_mask:0xf bank_mask:0xf bound_ctrl:1
	v_add_f32_dpp v119, v119, v119 row_ror:8 row_mask:0xf bank_mask:0xf bound_ctrl:1
	v_add_f32_dpp v121, v121, v121 row_ror:8 row_mask:0xf bank_mask:0xf bound_ctrl:1
	v_add_f32_dpp v123, v123, v123 row_ror:8 row_mask:0xf bank_mask:0xf bound_ctrl:1
	v_add_f32_dpp v125, v125, v125 row_ror:8 row_mask:0xf bank_mask:0xf bound_ctrl:1
	v_add_f32_dpp v127, v127, v127 row_ror:8 row_mask:0xf bank_mask:0xf bound_ctrl:1
	v_cndmask_b32_e64 v97, v97, v113, s[6:7]
	v_cndmask_b32_e64 v98, v98, v115, s[6:7]
	v_cndmask_b32_e64 v99, v99, v117, s[6:7]
	v_cndmask_b32_e64 v100, v100, v119, s[6:7]
	v_cndmask_b32_e64 v101, v101, v121, s[6:7]
	v_cndmask_b32_e64 v102, v102, v123, s[6:7]
	v_cndmask_b32_e64 v109, v109, v125, s[6:7]
	v_cndmask_b32_e64 v111, v111, v127, s[6:7]
	v_add_f32_dpp v97, v97, v97 row_half_mirror row_mask:0xf bank_mask:0xf bound_ctrl:1
	v_add_f32_dpp v98, v98, v98 row_half_mirror row_mask:0xf bank_mask:0xf bound_ctrl:1
	v_add_f32_dpp v99, v99, v99 row_half_mirror row_mask:0xf bank_mask:0xf bound_ctrl:1
	v_add_f32_dpp v100, v100, v100 row_half_mirror row_mask:0xf bank_mask:0xf bound_ctrl:1
	v_add_f32_dpp v101, v101, v101 row_half_mirror row_mask:0xf bank_mask:0xf bound_ctrl:1
	v_add_f32_dpp v102, v102, v102 row_half_mirror row_mask:0xf bank_mask:0xf bound_ctrl:1
	v_add_f32_dpp v109, v109, v109 row_half_mirror row_mask:0xf bank_mask:0xf bound_ctrl:1
	v_add_f32_dpp v111, v111, v111 row_half_mirror row_mask:0xf bank_mask:0xf bound_ctrl:1
	v_cndmask_b32_e64 v97, v97, v101, s[8:9]
	v_cndmask_b32_e64 v98, v98, v102, s[8:9]
	v_cndmask_b32_e64 v99, v99, v109, s[8:9]
	v_cndmask_b32_e64 v100, v100, v111, s[8:9]
	v_add_f32_dpp v97, v97, v97 quad_perm:[3,2,1,0] row_mask:0xf bank_mask:0xf bound_ctrl:1
	v_add_f32_dpp v98, v98, v98 quad_perm:[3,2,1,0] row_mask:0xf bank_mask:0xf bound_ctrl:1
	v_add_f32_dpp v99, v99, v99 quad_perm:[3,2,1,0] row_mask:0xf bank_mask:0xf bound_ctrl:1
	v_add_f32_dpp v100, v100, v100 quad_perm:[3,2,1,0] row_mask:0xf bank_mask:0xf bound_ctrl:1
	v_cndmask_b32_e64 v97, v97, v99, s[10:11]
	v_cndmask_b32_e64 v98, v98, v100, s[10:11]
	s_nop 1
	v_add_f32_dpp v97, v97, v97 quad_perm:[1,0,3,2] row_mask:0xf bank_mask:0xf bound_ctrl:1
	v_add_f32_dpp v98, v98, v98 quad_perm:[1,0,3,2] row_mask:0xf bank_mask:0xf bound_ctrl:1
	v_cndmask_b32_e64 v97, v97, v98, s[12:13]
	v_mov_b32_e32 v110, v97
	s_nop 1
	v_permlane16_swap_b32_e32 v97, v110
	v_add_f32_e32 v97, v97, v110
	v_mov_b32_e32 v110, v97
	s_nop 1
	v_permlane32_swap_b32_e32 v97, v110
	s_and_saveexec_b64 s[60:61], s[0:1]
	s_cbranch_execz .Lsmp_skip_0
	v_add_f32_e32 v97, v97, v110
	v_lshlrev_b32_e32 v46, 16, v170
	v_fma_f32 v48, v96, v46, v97
	v_mul_f32_e32 v46, 0x3d372713, v48
	v_mul_f32_e32 v46, v48, v46
	v_fma_f32 v46, v48, v46, v48
	v_mul_f32_e32 v46, 0xbfcc422a, v46
	v_mul_f32_e32 v46, 0x3fb8aa3b, v46
	v_exp_f32_e32 v46, v46
	v_lshl_add_u64 v[98:99], v[44:45], 0, s[44:45]
	v_add_f32_e32 v46, 1.0, v46
	v_rcp_f32_e32 v46, v46
	s_nop 0
	v_mul_f32_e32 v46, v48, v46
	v_cvt_pk_bf16_f32 v46, v46, v46
	global_store_short v[98:99], v46, off

.LBB0_1082:
	s_bitcmp1_b32 s100, 1
	s_cbranch_scc1 .Lsmp_static_ret
	s_mov_b64 s[4:5], exec
	v_readlane_b32 s44, v252, 45
	v_readlane_b32 s45, v252, 46
	s_and_b64 s[44:45], s[4:5], s[44:45]
	s_mov_b64 exec, s[44:45]
	s_cbranch_execz .LBB0_1071
	s_lshl_b32 s44, s2, 2
	s_add_i32 s44, s44, 0
	s_add_i32 s44, s44, 0x20170
	v_mov_b32_e32 v2, s44
	ds_write_b32 v2, v49
	s_branch .LBB0_1071
.Lsmp_static:
	s_mov_b32 s98, s62
	s_mov_b32 s99, s38
	s_or_b32 s100, s100, 3
	v_mov_b32_e32 v18, v228
	v_readlane_b32 s66, v252, 3
	v_readlane_b32 s67, v252, 47
	s_add_u32 s54, s72, 0xb01000
	s_addc_u32 s55, s73, 0
	s_add_u32 s56, s72, 0xb15000
	s_addc_u32 s57, s73, 0
	v_readlane_b32 s3, v252, 56
	v_ashrrev_i32_e32 v19, 31, v18
	s_bitcmp1_b32 s3, 2
	s_cselect_b64 s[58:59], -1, 0
	s_add_u32 s3, s72, 0xc300010
	v_lshl_add_u64 v[2:3], v[18:19], 1, s[72:73]
	s_mov_b64 s[4:5], 0xe500000
	v_and_b32_e32 v1, 15, v18
	v_cmp_gt_i32_e64 s[0:1], 16, v18
	v_cmp_eq_u32_e64 s[38:39], 15, v18
	v_and_b32_e32 v49, 8, v18
	v_cmp_ne_u32_e64 s[6:7], 0, v49
	v_and_b32_e32 v49, 4, v18
	v_cmp_ne_u32_e64 s[8:9], 0, v49
	v_and_b32_e32 v49, 2, v18
	v_cmp_ne_u32_e64 s[10:11], 0, v49
	v_and_b32_e32 v49, 1, v18
	v_cmp_ne_u32_e64 s[12:13], 0, v49
	v_and_b32_e32 v106, 15, v18
	v_lshlrev_b32_e32 v106, 1, v106
	v_cmp_eq_u32_e64 s[14:15], 10, v18
	v_cmp_eq_u32_e64 s[16:17], 9, v18
	v_cmp_eq_u32_e64 s[18:19], 8, v18
	v_cmp_eq_u32_e64 s[20:21], 7, v18
	v_cmp_eq_u32_e64 s[22:23], 6, v18
	v_cmp_eq_u32_e64 s[24:25], 5, v18
	v_cmp_eq_u32_e64 s[26:27], 4, v18
	v_cmp_eq_u32_e64 s[28:29], 3, v18
	v_cmp_eq_u32_e64 s[30:31], 2, v18
	s_mov_b32 s2, 1
	v_cmp_eq_u32_e64 s[34:35], 1, v18
	v_cmp_eq_u32_e64 s[36:37], 0, v18
	s_addc_u32 s33, s73, 0
	v_lshl_add_u64 v[20:21], v[2:3], 0, s[4:5]
	v_mov_b32_e32 v47, 0
	s_movk_i32 s62, 0x100
	s_mov_b32 s53, 0
	s_and_b32 s52, s98, 0x7ff
	s_lshr_b32 s52, s52, 3
	s_sub_i32 s52, s52, 0x100
	s_branch .Lsmp_item
.Lsmp_static_ret:
	s_andn2_b32 s100, s100, 2
	s_mov_b32 s62, s98
	s_mov_b32 s38, s99
	v_readlane_b32 s72, v252, 6
	v_readlane_b32 s73, v252, 7
	s_bitcmp1_b32 s100, 2
	s_cbranch_scc1 .Lp2_setup_go
	s_branch .Lsmp_dyn
